# gla_prep: next-item prefetch no longer drained right after issue (k values land in spare VGPRs, packed at the end of the item) so it overlaps the item's compute
# baseline (speedup 1.0000x reference)
; #define LAS __attribute__((address_space(3)))
; __device__ __forceinline__ bf16_t bf1(float v) { return (bf16_t)pk2(v, 0.f); }
; __device__ __forceinline__ void gla_prep(const Params& p, int l, LAS unsigned char* lds) {
;     ...
;         __syncthreads();
; #pragma unroll
;         for (int tt = 0; tt < 2; ++tt) { const int tile = wave * 2 + tt, it = tile >> 2, jt = tile & 3; f32x4 acc = {0.f, 0.f, 0.f, 0.f};
; #pragma unroll
;             for (int ks = 0; ks < 4; ++ks) { const bf16x8 a = *(const LAS bf16x8*)(qts + (it * 16 + fr) * 136 + ks * 32 + fq * 8), bb = *(const LAS bf16x8*)(kts + (jt * 16 + fr) * 136 + ks * 32 + fq * 8);
;                 acc = __builtin_amdgcn_mfma_f32_16x16x32_bf16(a, bb, acc, 0, 0, 0); }
; #pragma unroll
;             for (int jj = 0; jj < 4; ++jj) { const int i = it * 16 + fq * 4 + jj, jc = jt * 16 + fr; const bool keep = dir == 0 ? (jc <= i) : (jc >= i); ps[i * 72 + jc] = bf1(keep ? acc[jj] : 0.f); } }
;         __syncthreads();
;         bf16_t* qo = (bf16_t*)(C + C_QT) + (size_t)item * 8192; bf16_t* ko = (bf16_t*)(C + C_KHT) + (size_t)item * 8192; bf16_t* po = (bf16_t*)(C + C_P) + (size_t)item * 4096;
; #pragma unroll
;         for (int k = 0; k < 2; ++k) { const int q = tid + 512 * k; *(u32x4*)(qo + (q >> 4) * 128 + (q & 15) * 8) = *(const LAS u32x4*)(qts + (q >> 4) * 136 + (q & 15) * 8);
;             *(u32x4*)(ko + (q >> 3) * 64 + (q & 7) * 8) = *(const LAS u32x4*)(khs + (q >> 3) * 72 + (q & 7) * 8); }
;         *(u32x4*)(po + (tid >> 3) * 64 + (tid & 7) * 8) = *(const LAS u32x4*)(ps + (tid >> 3) * 72 + (tid & 7) * 8);
;         __syncthreads();
.LBB0_379:
	s_or_b64 exec, exec, s[70:71]
	s_waitcnt vmcnt(0)
	v_perm_b32 v147, v241, v240, s68
	v_perm_b32 v146, v243, v242, s68
	v_perm_b32 v145, v245, v244, s68
	v_perm_b32 v144, v247, v246, s68
	v_perm_b32 v143, v249, v248, s68
	v_perm_b32 v142, v251, v250, s68
	v_perm_b32 v141, v253, v252, s68
	v_perm_b32 v140, v255, v254, s68
	s_waitcnt lgkmcnt(0)
	s_barrier
	ds_read_b128 v[24:27], v8
	ds_read_b128 v[28:31], v79 offset:17408
	s_lshl_b64 s[70:71], s[74:75], 14
	s_waitcnt lgkmcnt(0)
	v_mfma_f32_16x16x32_bf16 v[24:27], v[24:27], v[28:31], 0
	ds_read_b128 v[28:31], v8 offset:64
	ds_read_b128 v[32:35], v79 offset:17472
	v_readlane_b32 s90, v238, 8
	v_add_u32_e32 v70, s96, v70
	s_waitcnt lgkmcnt(0)
	v_mfma_f32_16x16x32_bf16 v[24:27], v[28:31], v[32:35], v[24:27]
	ds_read_b128 v[28:31], v8 offset:128
	ds_read_b128 v[32:35], v79 offset:17536
	v_add_u32_e32 v72, s96, v72
	v_mov_b32_e32 v124, v114
	s_waitcnt lgkmcnt(0)
	v_mfma_f32_16x16x32_bf16 v[24:27], v[28:31], v[32:35], v[24:27]
	ds_read_b128 v[28:31], v8 offset:192
	ds_read_b128 v[32:35], v79 offset:17600
	v_mov_b32_e32 v121, v115
	v_mov_b32_e32 v119, v117
	s_waitcnt lgkmcnt(0)
	v_mfma_f32_16x16x32_bf16 v[24:27], v[28:31], v[32:35], v[24:27]
	v_cndmask_b32_e64 v28, 0, 1, s[20:21]
	v_cndmask_b32_e64 v29, 0, 1, s[22:23]
	v_cndmask_b32_e64 v28, v29, v28, s[54:55]
	v_and_b32_e32 v28, 1, v28
	v_cmp_eq_u32_e32 vcc, 1, v28
	s_nop 2
	v_cvt_pk_bf16_f32 v24, v24, s0
	v_cndmask_b32_e64 v28, 0, 1, s[26:27]
	v_cndmask_b32_e32 v24, 0, v24, vcc
	ds_write_b16 v80, v24 offset:53248
	v_cndmask_b32_e64 v24, 0, 1, s[24:25]
	v_cndmask_b32_e64 v24, v28, v24, s[54:55]
	v_and_b32_e32 v24, 1, v24
	v_cmp_eq_u32_e32 vcc, 1, v24
	v_cvt_pk_bf16_f32 v24, v25, s0
	v_cndmask_b32_e64 v25, 0, 1, s[30:31]
	v_cndmask_b32_e32 v24, 0, v24, vcc
	ds_write_b16 v80, v24 offset:53392
	v_cndmask_b32_e64 v24, 0, 1, s[28:29]
	v_cndmask_b32_e64 v24, v25, v24, s[54:55]
	v_and_b32_e32 v24, 1, v24
	v_cmp_eq_u32_e32 vcc, 1, v24
	v_cvt_pk_bf16_f32 v24, v26, s0
	v_cndmask_b32_e64 v25, 0, 1, s[36:37]
	v_cndmask_b32_e32 v24, 0, v24, vcc
	ds_write_b16 v80, v24 offset:53536
	v_cndmask_b32_e64 v24, 0, 1, s[34:35]
	v_cndmask_b32_e64 v24, v25, v24, s[54:55]
	v_and_b32_e32 v24, 1, v24
	v_cmp_eq_u32_e32 vcc, 1, v24
	v_cvt_pk_bf16_f32 v24, v27, s0
	v_mov_b32_e32 v116, v120
	v_cndmask_b32_e32 v24, 0, v24, vcc
	ds_write_b16 v80, v24 offset:53680
	ds_read_b128 v[24:27], v8
	ds_read_b128 v[28:31], v79 offset:21760
	s_waitcnt lgkmcnt(0)
	v_mfma_f32_16x16x32_bf16 v[24:27], v[24:27], v[28:31], 0
	ds_read_b128 v[28:31], v8 offset:64
	ds_read_b128 v[32:35], v79 offset:21824
	v_mov_b32_e32 v111, v123
	v_mov_b32_e32 v109, v125
	s_waitcnt lgkmcnt(0)
	v_mfma_f32_16x16x32_bf16 v[24:27], v[28:31], v[32:35], v[24:27]
	ds_read_b128 v[28:31], v8 offset:128
	ds_read_b128 v[32:35], v79 offset:21888
	v_mov_b32_e32 v107, v126
	v_mov_b32_e32 v105, v128
	s_waitcnt lgkmcnt(0)
	v_mfma_f32_16x16x32_bf16 v[24:27], v[28:31], v[32:35], v[24:27]
	ds_read_b128 v[28:31], v8 offset:192
	ds_read_b128 v[32:35], v79 offset:21952
	v_mov_b32_e32 v97, v129
	v_mov_b32_e32 v93, v131
	s_waitcnt lgkmcnt(0)
	v_mfma_f32_16x16x32_bf16 v[24:27], v[28:31], v[32:35], v[24:27]
	v_cndmask_b32_e64 v28, 0, 1, s[38:39]
	v_cndmask_b32_e64 v29, 0, 1, s[40:41]
	v_cndmask_b32_e64 v28, v29, v28, s[54:55]
	v_and_b32_e32 v28, 1, v28
	v_cmp_eq_u32_e32 vcc, 1, v28
	s_nop 2
	v_cvt_pk_bf16_f32 v24, v24, s0
	v_cndmask_b32_e64 v28, 0, 1, s[44:45]
	v_cndmask_b32_e32 v24, 0, v24, vcc
	ds_write_b16 v80, v24 offset:53280
	v_cndmask_b32_e64 v24, 0, 1, s[42:43]
	v_cndmask_b32_e64 v24, v28, v24, s[54:55]
	v_and_b32_e32 v24, 1, v24
	v_cmp_eq_u32_e32 vcc, 1, v24
	v_cvt_pk_bf16_f32 v24, v25, s0
	v_cndmask_b32_e64 v25, 0, 1, s[48:49]
	v_cndmask_b32_e32 v24, 0, v24, vcc
	ds_write_b16 v80, v24 offset:53424
	v_cndmask_b32_e64 v24, 0, 1, s[46:47]
	v_cndmask_b32_e64 v24, v25, v24, s[54:55]
	v_and_b32_e32 v24, 1, v24
	v_cmp_eq_u32_e32 vcc, 1, v24
	v_cvt_pk_bf16_f32 v24, v26, s0
	v_cndmask_b32_e64 v25, 0, 1, s[52:53]
	v_cndmask_b32_e32 v24, 0, v24, vcc
	ds_write_b16 v80, v24 offset:53568
	v_cndmask_b32_e64 v24, 0, 1, s[50:51]
	v_cndmask_b32_e64 v24, v25, v24, s[54:55]
	v_and_b32_e32 v24, 1, v24
	v_cmp_eq_u32_e32 vcc, 1, v24
	v_cvt_pk_bf16_f32 v24, v27, s0
	v_lshl_add_u64 v[28:29], v[10:11], 0, s[70:71]
	v_cndmask_b32_e32 v24, 0, v24, vcc
	ds_write_b16 v80, v24 offset:53712
	s_waitcnt lgkmcnt(0)
	s_barrier
	ds_read_b128 v[24:27], v81
	v_lshl_add_u64 v[32:33], v[18:19], 1, v[28:29]
	v_lshl_add_u64 v[30:31], v[12:13], 0, s[70:71]
	v_lshl_add_u64 v[28:29], v[20:21], 1, v[28:29]
	s_lshl_b64 s[54:55], s[74:75], 13
	s_waitcnt lgkmcnt(0)
	global_store_dwordx4 v[32:33], v[24:27], off
	ds_read_b128 v[24:27], v9 offset:34816
	v_lshl_add_u64 v[32:33], v[14:15], 1, v[30:31]
	s_andn2_b64 vcc, exec, s[88:89]
	v_mov_b32_e32 v89, v132
	v_mov_b32_e32 v88, v133
	s_waitcnt lgkmcnt(0)
	global_store_dwordx4 v[32:33], v[24:27], off
	ds_read_b128 v[24:27], v82
	v_mov_b32_e32 v87, v135
	v_mov_b32_e32 v86, v137
	v_mov_b32_e32 v85, v138
	v_mov_b32_e32 v84, v139
	s_waitcnt lgkmcnt(0)
	global_store_dwordx4 v[28:29], v[24:27], off
	ds_read_b128 v[24:27], v83 offset:34816
	v_lshl_add_u64 v[28:29], v[22:23], 1, v[30:31]
	v_mov_b32_e32 v54, v64
	s_mov_b32 s74, s97
	v_mov_b32_e32 v136, v147
	s_waitcnt lgkmcnt(0)
	global_store_dwordx4 v[28:29], v[24:27], off
	ds_read_b128 v[24:27], v9 offset:53248
	v_lshl_add_u64 v[28:29], v[16:17], 0, s[54:55]
	v_mov_b32_e32 v134, v146
	v_mov_b32_e32 v130, v145
	v_mov_b32_e32 v127, v144
	s_waitcnt lgkmcnt(0)
	global_store_dwordx4 v[28:29], v[24:27], off
	v_mov_b32_e32 v122, v143
	v_mov_b32_e32 v118, v142
	v_mov_b32_e32 v113, v141
	v_mov_b32_e32 v112, v140
	v_mov_b32_e32 v24, v103
	v_mov_b32_e32 v25, v110
	v_mov_b32_e32 v28, v102
	v_mov_b32_e32 v29, v108
	v_mov_b32_e32 v30, v101
	v_mov_b32_e32 v31, v104
	v_mov_b32_e32 v26, v100
	v_mov_b32_e32 v27, v106
	v_mov_b32_e32 v32, v94
	v_mov_b32_e32 v33, v99
	v_mov_b32_e32 v34, v92
	v_mov_b32_e32 v35, v98
	v_mov_b32_e32 v38, v91
	v_mov_b32_e32 v39, v96
	v_mov_b32_e32 v36, v90
	v_mov_b32_e32 v37, v95
	v_readlane_b32 s88, v238, 6
	v_readlane_b32 s91, v238, 9
	s_barrier
	v_readlane_b32 s89, v238, 7
	s_cbranch_vccz .LBB0_395

.LBB0_387:
	s_or_b64 exec, exec, s[54:55]
	s_lshl_b32 s54, s71, 6
	s_and_b32 s54, s54, 0x180
	v_or_b32_e32 v41, s1, v41
	v_or_b32_e32 v48, s54, v71
	v_lshl_or_b32 v64, v41, 9, v48
	v_lshl_add_u64 v[42:43], v[64:65], 2, s[60:61]
	v_add_co_u32_e32 v44, vcc, 0x1000, v42
	s_movk_i32 s55, 0x2000
	s_nop 0
	v_addc_co_u32_e32 v45, vcc, 0, v43, vcc
	global_load_dword v91, v[42:43], off
	global_load_dword v90, v[42:43], off offset:2048
	global_load_dword v92, v[44:45], off
	global_load_dword v94, v[44:45], off offset:2048
	v_add_co_u32_e32 v44, vcc, s55, v42
	s_movk_i32 s55, 0x3000
	s_nop 0
	v_addc_co_u32_e32 v45, vcc, 0, v43, vcc
	v_add_co_u32_e32 v46, vcc, s55, v42
	s_movk_i32 s55, 0x5000
	s_nop 0
	v_addc_co_u32_e32 v47, vcc, 0, v43, vcc
	global_load_dword v96, v[46:47], off offset:-4096
	global_load_dword v95, v[44:45], off offset:2048
	global_load_dword v98, v[46:47], off
	global_load_dword v99, v[46:47], off offset:2048
	v_add_co_u32_e32 v44, vcc, s33, v42
	v_add3_u32 v40, s83, v72, v40
	s_nop 0
	v_addc_co_u32_e32 v45, vcc, 0, v43, vcc
	v_add_co_u32_e32 v46, vcc, s55, v42
	s_movk_i32 s55, 0x6000
	s_nop 0
	v_addc_co_u32_e32 v47, vcc, 0, v43, vcc
	global_load_dword v101, v[46:47], off offset:-4096
	global_load_dword v100, v[44:45], off offset:2048
	global_load_dword v102, v[46:47], off
	global_load_dword v103, v[46:47], off offset:2048
	v_add_co_u32_e32 v44, vcc, s55, v42
	s_movk_i32 s55, 0x7000
	s_nop 0
	v_addc_co_u32_e32 v45, vcc, 0, v43, vcc
	v_add_co_u32_e32 v42, vcc, s55, v42
	s_lshl_b32 s55, s70, 9
	s_or_b32 s55, s55, s65
	s_or_b32 s54, s55, s54
	v_addc_co_u32_e32 v43, vcc, 0, v43, vcc
	v_or_b32_e32 v64, s54, v71
	global_load_dword v104, v[42:43], off offset:-4096
	global_load_dword v106, v[44:45], off offset:2048
	global_load_dword v108, v[42:43], off
	global_load_dword v110, v[42:43], off offset:2048
	v_lshl_add_u64 v[42:43], v[64:65], 2, s[62:63]
	v_ashrrev_i32_e32 v41, 31, v40
	global_load_dword v64, v[42:43], off
	v_lshlrev_b64 v[42:43], 10, v[40:41]
	v_lshlrev_b32_e32 v46, 1, v48
	v_or_b32_e32 v42, v42, v46
	v_lshl_add_u64 v[44:45], s[58:59], 0, v[42:43]
	v_lshl_add_u64 v[42:43], s[92:93], 0, v[42:43]
	global_load_ushort v114, v[44:45], off
	global_load_ushort v240, v[42:43], off
	v_add_u32_e32 v42, 1, v40
	v_ashrrev_i32_e32 v43, 31, v42
	v_lshlrev_b64 v[42:43], 10, v[42:43]
	v_or_b32_e32 v42, v42, v46
	v_lshl_add_u64 v[44:45], s[58:59], 0, v[42:43]
	v_lshl_add_u64 v[42:43], s[92:93], 0, v[42:43]
	global_load_ushort v115, v[44:45], off
	global_load_ushort v241, v[42:43], off
	v_add_u32_e32 v42, 2, v40
	v_ashrrev_i32_e32 v43, 31, v42
	v_lshlrev_b64 v[42:43], 10, v[42:43]
	v_or_b32_e32 v42, v42, v46
	v_lshl_add_u64 v[44:45], s[58:59], 0, v[42:43]
	v_lshl_add_u64 v[42:43], s[92:93], 0, v[42:43]
	global_load_ushort v117, v[44:45], off
	global_load_ushort v242, v[42:43], off
	v_add_u32_e32 v42, 3, v40
	v_ashrrev_i32_e32 v43, 31, v42
	v_lshlrev_b64 v[42:43], 10, v[42:43]
	v_or_b32_e32 v42, v42, v46
	v_lshl_add_u64 v[44:45], s[58:59], 0, v[42:43]
	v_lshl_add_u64 v[42:43], s[92:93], 0, v[42:43]
	global_load_ushort v120, v[44:45], off
	global_load_ushort v243, v[42:43], off
	v_add_u32_e32 v42, 4, v40
	v_ashrrev_i32_e32 v43, 31, v42
	v_lshlrev_b64 v[42:43], 10, v[42:43]
	v_or_b32_e32 v42, v42, v46
	v_lshl_add_u64 v[44:45], s[58:59], 0, v[42:43]
	v_lshl_add_u64 v[42:43], s[92:93], 0, v[42:43]
	global_load_ushort v123, v[44:45], off
	global_load_ushort v244, v[42:43], off
	v_add_u32_e32 v42, 5, v40
	v_ashrrev_i32_e32 v43, 31, v42
	v_lshlrev_b64 v[42:43], 10, v[42:43]
	v_or_b32_e32 v42, v42, v46
	v_lshl_add_u64 v[44:45], s[58:59], 0, v[42:43]
	v_lshl_add_u64 v[42:43], s[92:93], 0, v[42:43]
	global_load_ushort v125, v[44:45], off
	global_load_ushort v245, v[42:43], off
	v_add_u32_e32 v42, 6, v40
	v_ashrrev_i32_e32 v43, 31, v42
	v_lshlrev_b64 v[42:43], 10, v[42:43]
	v_or_b32_e32 v42, v42, v46
	v_lshl_add_u64 v[44:45], s[58:59], 0, v[42:43]
	v_lshl_add_u64 v[42:43], s[92:93], 0, v[42:43]
	global_load_ushort v126, v[44:45], off
	global_load_ushort v246, v[42:43], off
	v_add_u32_e32 v42, 7, v40
	v_ashrrev_i32_e32 v43, 31, v42
	v_lshlrev_b64 v[42:43], 10, v[42:43]
	v_or_b32_e32 v42, v42, v46
	v_lshl_add_u64 v[44:45], s[58:59], 0, v[42:43]
	v_lshl_add_u64 v[42:43], s[92:93], 0, v[42:43]
	global_load_ushort v128, v[44:45], off
	global_load_ushort v247, v[42:43], off
	v_add_u32_e32 v42, 8, v40
	v_ashrrev_i32_e32 v43, 31, v42
	v_lshlrev_b64 v[42:43], 10, v[42:43]
	v_or_b32_e32 v42, v42, v46
	v_lshl_add_u64 v[44:45], s[58:59], 0, v[42:43]
	v_lshl_add_u64 v[42:43], s[92:93], 0, v[42:43]
	global_load_ushort v129, v[44:45], off
	global_load_ushort v248, v[42:43], off
	v_add_u32_e32 v42, 9, v40
	v_ashrrev_i32_e32 v43, 31, v42
	v_lshlrev_b64 v[42:43], 10, v[42:43]
	v_or_b32_e32 v42, v42, v46
	v_lshl_add_u64 v[44:45], s[58:59], 0, v[42:43]
	v_lshl_add_u64 v[42:43], s[92:93], 0, v[42:43]
	global_load_ushort v131, v[44:45], off
	global_load_ushort v249, v[42:43], off
	v_add_u32_e32 v42, 10, v40
	v_ashrrev_i32_e32 v43, 31, v42
	v_lshlrev_b64 v[42:43], 10, v[42:43]
	v_or_b32_e32 v42, v42, v46
	v_lshl_add_u64 v[44:45], s[58:59], 0, v[42:43]
	v_lshl_add_u64 v[42:43], s[92:93], 0, v[42:43]
	global_load_ushort v132, v[44:45], off
	global_load_ushort v250, v[42:43], off
	v_add_u32_e32 v42, 11, v40
	v_ashrrev_i32_e32 v43, 31, v42
	v_lshlrev_b64 v[42:43], 10, v[42:43]
	v_or_b32_e32 v42, v42, v46
	v_lshl_add_u64 v[44:45], s[58:59], 0, v[42:43]
	v_lshl_add_u64 v[42:43], s[92:93], 0, v[42:43]
	global_load_ushort v133, v[44:45], off
	global_load_ushort v251, v[42:43], off
	v_add_u32_e32 v42, 12, v40
	v_ashrrev_i32_e32 v43, 31, v42
	v_lshlrev_b64 v[42:43], 10, v[42:43]
	v_or_b32_e32 v42, v42, v46
	v_lshl_add_u64 v[44:45], s[58:59], 0, v[42:43]
	v_lshl_add_u64 v[42:43], s[92:93], 0, v[42:43]
	global_load_ushort v135, v[44:45], off
	global_load_ushort v252, v[42:43], off
	v_add_u32_e32 v42, 13, v40
	v_ashrrev_i32_e32 v43, 31, v42
	v_lshlrev_b64 v[42:43], 10, v[42:43]
	v_or_b32_e32 v42, v42, v46
	v_lshl_add_u64 v[44:45], s[58:59], 0, v[42:43]
	v_lshl_add_u64 v[42:43], s[92:93], 0, v[42:43]
	global_load_ushort v137, v[44:45], off
	global_load_ushort v253, v[42:43], off
	v_add_u32_e32 v42, 14, v40
	v_ashrrev_i32_e32 v43, 31, v42
	v_add_u32_e32 v40, 15, v40
	v_lshlrev_b64 v[42:43], 10, v[42:43]
	v_ashrrev_i32_e32 v41, 31, v40
	v_or_b32_e32 v42, v42, v46
	v_lshlrev_b64 v[40:41], 10, v[40:41]
	v_lshl_add_u64 v[44:45], s[58:59], 0, v[42:43]
	v_lshl_add_u64 v[42:43], s[92:93], 0, v[42:43]
	v_or_b32_e32 v40, v40, v46
	global_load_ushort v138, v[44:45], off
	global_load_ushort v254, v[42:43], off
	v_lshl_add_u64 v[42:43], s[58:59], 0, v[40:41]
	v_lshl_add_u64 v[40:41], s[92:93], 0, v[40:41]
	global_load_ushort v139, v[42:43], off
	global_load_ushort v255, v[40:41], off
	s_branch .LBB0_389
